# attention query / gate row loads non-temporal (read once)
# baseline (speedup 1.0000x reference)
.LBB0_254:
	s_or_b64 exec, exec, s[2:3]
	s_lshl_b32 s2, s50, 4
	v_readlane_b32 s3, v252, 46
	s_add_i32 s2, s2, s3
	v_or_b32_e32 v2, s2, v84
	v_ashrrev_i32_e32 v3, 31, v2
	v_readlane_b32 s2, v252, 45
	s_movk_i32 s4, 0x4800
	s_nop 0
	v_lshlrev_b64 v[2:3], s2, v[2:3]
	v_readlane_b32 s2, v252, 43
	v_readlane_b32 s3, v252, 44
	s_nop 1
	v_lshl_add_u64 v[2:3], v[2:3], 0, s[2:3]
	v_readlane_b32 s2, v252, 48
	v_readlane_b32 s3, v252, 49
	s_nop 1
	v_mov_b64_e32 v[28:29], s[2:3]
	v_mad_u64_u32 v[28:29], s[2:3], v2, s4, v[28:29]
	v_mov_b32_e32 v2, v29
	v_mad_u64_u32 v[2:3], s[2:3], v3, s4, v[2:3]
	v_mov_b32_e32 v29, v2
	v_lshlrev_b32_e32 v2, 4, v86
	v_mov_b32_e32 v3, v0
	v_lshl_add_u64 v[2:3], v[28:29], 0, v[2:3]
	global_load_dwordx4 v[48:51], v[2:3], off nt
	global_load_dwordx4 v[52:55], v[2:3], off offset:64 nt

.LBB0_264:
	s_or_b64 exec, exec, s[2:3]
	s_lshl_b32 s2, s50, 4
	v_readlane_b32 s3, v252, 55
	s_add_i32 s2, s2, s3
	v_or_b32_e32 v2, s2, v84
	v_ashrrev_i32_e32 v3, 31, v2
	v_readlane_b32 s2, v252, 54
	s_movk_i32 s4, 0x4800
	s_nop 0
	v_lshlrev_b64 v[2:3], s2, v[2:3]
	v_readlane_b32 s2, v252, 52
	v_readlane_b32 s3, v252, 53
	s_nop 1
	v_lshl_add_u64 v[2:3], v[2:3], 0, s[2:3]
	v_readlane_b32 s2, v252, 57
	v_readlane_b32 s3, v252, 58
	s_nop 1
	v_mov_b64_e32 v[76:77], s[2:3]
	v_mad_u64_u32 v[76:77], s[2:3], v2, s4, v[76:77]
	v_mov_b32_e32 v2, v77
	v_mad_u64_u32 v[2:3], s[2:3], v3, s4, v[2:3]
	v_mov_b32_e32 v77, v2
	v_lshlrev_b32_e32 v2, 4, v86
	v_mov_b32_e32 v3, v0
	v_lshl_add_u64 v[2:3], v[76:77], 0, v[2:3]
	global_load_dwordx4 v[76:79], v[2:3], off nt
	global_load_dwordx4 v[80:83], v[2:3], off offset:64 nt

; #define LAS __attribute__((address_space(3)))
; __device__ __forceinline__ float bflo(unsigned u) { return __uint_as_float(u << 16); }
; __device__ __forceinline__ float bfhi(unsigned u) { return __uint_as_float(u & 0xffff0000u); }
; __device__ __forceinline__ unsigned pk2(float lo, float hi) { f32x2_t v = {lo, hi}; bf16x2_t b = __builtin_convertvector(v, bf16x2_t); return __builtin_bit_cast(unsigned, b); }
; __device__ __forceinline__ void attn_phase(LAS unsigned char* lds, const bf16* PROJ, const bf16* Ygate, bf16* OG0, bf16* OG1, bf16* OG2, float* LSE, const float* qnw, const float* knw, int bx, int G) {
;     ...
;         const int sub = t & 15, gi = (t >> 4) % 3, bh = t / 48, h = bh & 15, bl = bh >> 4;
;         const int sh = 2 * gi, d = 1 << sh, r = sub & (d - 1), n = sub >> sh;
;         const float ad = exp2f(-8.f * (float)(gi * 16 + h + 1) / 48.f) * (float)d;
;         bf16* OG = gi == 0 ? OG0 : (gi == 1 ? OG1 : OG2);
;         {
;             const f32x4 kw0 = *(const f32x4*)(knw + gi * 64 + 8 * oct), kw1 = *(const f32x4*)(knw + gi * 64 + 8 * oct + 4);
; #pragma unroll
;             for (int jj = 0; jj < 4; ++jj) {
;                 const int key = (tid >> 3) + 64 * jj; const v4u kq = kr[half][jj];
;                 float kf[8] = {bflo(kq.x), bfhi(kq.x), bflo(kq.y), bfhi(kq.y), bflo(kq.z), bfhi(kq.z), bflo(kq.w), bfhi(kq.w)};
;                 float ss = 0.f;
; #pragma unroll
;                 for (int e = 0; e < 8; ++e) ss += kf[e] * kf[e];
;                 ss += __shfl_xor(ss, 1); ss += __shfl_xor(ss, 2); ss += __shfl_xor(ss, 4);
;                 const float rs = rsqrtf(ss * (1.f / 64.f) + EPS);
;                 v4u ko; ko.x = pk2(kf[0] * rs * kw0[0], kf[1] * rs * kw0[1]); ko.y = pk2(kf[2] * rs * kw0[2], kf[3] * rs * kw0[3]);
;                 ko.z = pk2(kf[4] * rs * kw1[0], kf[5] * rs * kw1[1]); ko.w = pk2(kf[6] * rs * kw1[2], kf[7] * rs * kw1[3]);
;                 *(LAS v4u*)(Ks + key * 72 + 8 * oct) = ko;
;                 *(LAS v4u*)(Vs + key * 80 + 8 * oct) = vr[half][jj];
;             }
.LBB0_269:
	s_ashr_i32 s0, s51, 4
	s_mul_hi_i32 s1, s0, 0x55555556
	s_lshr_b32 s2, s1, 31
	s_add_i32 s1, s1, s2
	s_mul_i32 s1, s1, 3
	s_sub_i32 s2, s0, s1
	s_mul_hi_i32 s0, s51, 0x2aaaaaab
	s_lshl_b32 s3, s2, 1
	s_and_b32 s20, s51, 15
	s_lshr_b32 s1, s0, 31
	s_ashr_i32 s21, s0, 3
	s_bfm_b32 s0, s3, 0
	s_and_b32 s22, s0, s20
	s_lshl_b32 s0, s2, 6
	s_add_i32 s21, s21, s1
	s_ashr_i32 s1, s0, 31
	s_lshl_b64 s[24:25], s[0:1], 2
	v_lshl_add_u64 v[2:3], v[110:111], 0, s[24:25]
	global_load_dwordx4 v[84:87], v[2:3], off offset:16
	global_load_dwordx4 v[88:91], v[2:3], off
	s_waitcnt vmcnt(5)
	v_lshlrev_b32_e32 v102, 16, v8
	v_and_b32_e32 v103, 0xffff0000, v8
	v_lshlrev_b32_e32 v98, 16, v9
	v_and_b32_e32 v99, 0xffff0000, v9
	v_pk_mul_f32 v[104:105], v[102:103], v[102:103]
	v_pk_mul_f32 v[100:101], v[98:99], v[98:99]
	v_add_f32_e32 v1, v104, v105
	v_lshlrev_b32_e32 v94, 16, v10
	v_and_b32_e32 v95, 0xffff0000, v10
	v_add_f32_e32 v1, v100, v1
	v_pk_mul_f32 v[96:97], v[94:95], v[94:95]
	v_add_f32_e32 v1, v101, v1
	v_lshlrev_b32_e32 v2, 16, v11
	v_and_b32_e32 v3, 0xffff0000, v11
	v_add_f32_e32 v1, v96, v1
	v_pk_mul_f32 v[92:93], v[2:3], v[2:3]
	v_add_f32_e32 v1, v97, v1
	v_add_f32_e32 v1, v92, v1
	v_add_f32_e32 v1, v93, v1
	s_nop 1
	v_mov_b32_dpp v92, v1 quad_perm:[1,0,3,2] row_mask:0xf bank_mask:0xf
	v_lshlrev_b32_e32 v156, 16, v20
	v_and_b32_e32 v157, 0xffff0000, v20
	v_lshlrev_b32_e32 v152, 16, v21
	v_and_b32_e32 v153, 0xffff0000, v21
	s_waitcnt lgkmcnt(0)
	v_add_f32_e32 v1, v1, v92
	s_nop 1
	v_mov_b32_dpp v92, v1 quad_perm:[2,3,0,1] row_mask:0xf bank_mask:0xf
	v_pk_mul_f32 v[158:159], v[156:157], v[156:157]
	v_pk_mul_f32 v[154:155], v[152:153], v[152:153]
	v_mov_b32_e32 v162, v158
	v_lshlrev_b32_e32 v136, 16, v22
	s_waitcnt lgkmcnt(0)
	v_add_f32_e32 v1, v1, v92
	s_nop 1
	v_mov_b32_dpp v92, v1 row_half_mirror row_mask:0xf bank_mask:0xf
	v_and_b32_e32 v137, 0xffff0000, v22
	v_mov_b32_e32 v158, v154
	v_pk_mul_f32 v[150:151], v[136:137], v[136:137]
	v_lshlrev_b32_e32 v106, 16, v23
	s_waitcnt lgkmcnt(0)
	v_add_f32_e32 v1, v1, v92
	v_fmamk_f32 v1, v1, 0x3c800000, v139
	v_and_b32_e32 v107, 0xffff0000, v23
	v_rsq_f32_e32 v1, v1
	v_pk_mul_f32 v[134:135], v[106:107], v[106:107]
	s_mov_b32 s0, 0x358637bd
	s_mov_b32 s26, 0x3c800000
	s_nop 0
	v_mov_b32_e32 v96, v1
	v_pk_mul_f32 v[92:93], v[96:97], v[102:103] op_sel_hi:[0,1]
	v_pk_mul_f32 v[98:99], v[96:97], v[98:99] op_sel_hi:[0,1]
	v_pk_mul_f32 v[94:95], v[96:97], v[94:95] op_sel_hi:[0,1]
	v_pk_mul_f32 v[2:3], v[96:97], v[2:3] op_sel_hi:[0,1]
	v_lshlrev_b32_e32 v102, 16, v4
	v_and_b32_e32 v103, 0xffff0000, v4
	v_pk_mul_f32 v[104:105], v[102:103], v[102:103]
	s_waitcnt vmcnt(3)
	v_and_b32_e32 v179, 0xffff0000, v48
	v_mov_b32_e32 v163, v104
	v_mov_b32_e32 v104, v159
	v_pk_add_f32 v[104:105], v[162:163], v[104:105]
	v_lshlrev_b32_e32 v178, 16, v48
	v_mul_f32_e32 v240, v179, v179
	v_lshlrev_b32_e32 v176, 16, v49
	v_and_b32_e32 v177, 0xffff0000, v49
	v_pk_fma_f32 v[240:241], v[178:179], v[178:179], v[240:241] op_sel_hi:[1,1,0]
	v_mul_f32_e32 v242, v177, v177
	v_pk_fma_f32 v[240:241], v[176:177], v[176:177], v[240:241]
	v_lshlrev_b32_e32 v174, 16, v50
	v_and_b32_e32 v175, 0xffff0000, v50
	v_pk_add_f32 v[240:241], v[242:243], v[240:241] op_sel_hi:[0,1]
	v_pk_fma_f32 v[240:241], v[174:175], v[174:175], v[240:241]
	v_mul_f32_e32 v242, v175, v175
	v_lshlrev_b32_e32 v172, 16, v51
	v_and_b32_e32 v173, 0xffff0000, v51
	v_pk_add_f32 v[240:241], v[242:243], v[240:241] op_sel_hi:[0,1]
	v_add_u32_e32 v231, v113, v188
	v_lshlrev_b32_e32 v162, 16, v40
	v_and_b32_e32 v163, 0xffff0000, v40
	s_waitcnt vmcnt(2)
	v_lshlrev_b32_e32 v170, 16, v52
	s_waitcnt vmcnt(1)
	v_pk_mul_f32 v[94:95], v[84:85], v[94:95]
	s_waitcnt vmcnt(0)
	v_pk_mul_f32 v[92:93], v[88:89], v[92:93]
	v_pk_mul_f32 v[98:99], v[90:91], v[98:99]
	v_cvt_pk_bf16_f32 v92, v92, v93
	v_cvt_pk_bf16_f32 v93, v98, v99
	v_pk_mul_f32 v[2:3], v[86:87], v[2:3]
	v_lshlrev_b32_e32 v98, 16, v5
	v_and_b32_e32 v99, 0xffff0000, v5
	v_cvt_pk_bf16_f32 v94, v94, v95
	v_cvt_pk_bf16_f32 v95, v2, v3
	v_pk_mul_f32 v[100:101], v[98:99], v[98:99]
	ds_write_b128 v229, v[92:95]
	v_lshlrev_b32_e32 v94, 16, v6
	v_and_b32_e32 v95, 0xffff0000, v6
	v_mov_b32_e32 v159, v100
	v_pk_mul_f32 v[96:97], v[94:95], v[94:95]
	v_pk_add_f32 v[104:105], v[158:159], v[104:105]
	v_mov_b32_e32 v100, v155
	v_lshlrev_b32_e32 v2, 16, v7
	v_and_b32_e32 v3, 0xffff0000, v7
	v_pk_add_f32 v[100:101], v[100:101], v[104:105]
	v_mov_b32_e32 v104, v150
	v_mov_b32_e32 v105, v96
	v_pk_mul_f32 v[92:93], v[2:3], v[2:3]
	v_pk_add_f32 v[100:101], v[104:105], v[100:101]
	v_mov_b32_e32 v96, v151
	v_pk_add_f32 v[96:97], v[96:97], v[100:101]
	v_mov_b32_e32 v100, v134
	v_mov_b32_e32 v101, v92
	v_pk_add_f32 v[96:97], v[100:101], v[96:97]
	v_mov_b32_e32 v92, v135
	v_pk_add_f32 v[92:93], v[92:93], v[96:97]
	s_nop 1
	v_mov_b32_dpp v97, v93 quad_perm:[1,0,3,2] row_mask:0xf bank_mask:0xf
	s_nop 1
	v_mov_b32_dpp v96, v92 quad_perm:[1,0,3,2] row_mask:0xf bank_mask:0xf
	v_mov_b64_e32 v[134:135], s[0:1]
	v_and_b32_e32 v171, 0xffff0000, v52
	v_pk_fma_f32 v[240:241], v[172:173], v[172:173], v[240:241]
	v_mul_f32_e32 v242, v173, v173
	s_waitcnt lgkmcnt(0)
	v_pk_add_f32 v[92:93], v[92:93], v[96:97]
	s_nop 1
	v_mov_b32_dpp v97, v93 quad_perm:[2,3,0,1] row_mask:0xf bank_mask:0xf
	s_nop 1
	v_mov_b32_dpp v96, v92 quad_perm:[2,3,0,1] row_mask:0xf bank_mask:0xf
	ds_write_b128 v231, v[12:15] offset:36864
	v_pk_mul_f32 v[180:181], v[162:163], v[162:163]
	v_pk_mul_f32 v[238:239], v[170:171], v[170:171]
	v_pk_add_f32 v[240:241], v[242:243], v[240:241] op_sel_hi:[0,1]
	s_waitcnt lgkmcnt(1)
; #define LAS __attribute__((address_space(3)))
; __device__ __forceinline__ void attn_phase(LAS unsigned char* lds, const bf16* PROJ, const bf16* Ygate, bf16* OG0, bf16* OG1, bf16* OG2, float* LSE, const float* qnw, const float* knw, int bx, int G) {
;     ...
;             const f32x4 kw0 = *(const f32x4*)(knw + gi * 64 + 8 * oct), kw1 = *(const f32x4*)(knw + gi * 64 + 8 * oct + 4);
; #pragma unroll
;             for (int jj = 0; jj < 4; ++jj) {
;                 const int key = (tid >> 3) + 64 * jj; const v4u kq = kr[half][jj];
;                 float kf[8] = {bflo(kq.x), bfhi(kq.x), bflo(kq.y), bfhi(kq.y), bflo(kq.z), bfhi(kq.z), bflo(kq.w), bfhi(kq.w)};
;                 float ss = 0.f;
; #pragma unroll
;                 for (int e = 0; e < 8; ++e) ss += kf[e] * kf[e];
;                 ss += __shfl_xor(ss, 1); ss += __shfl_xor(ss, 2); ss += __shfl_xor(ss, 4);
;                 const float rs = rsqrtf(ss * (1.f / 64.f) + EPS);
;                 v4u ko; ko.x = pk2(kf[0] * rs * kw0[0], kf[1] * rs * kw0[1]); ko.y = pk2(kf[2] * rs * kw0[2], kf[3] * rs * kw0[3]);
;                 ko.z = pk2(kf[4] * rs * kw1[0], kf[5] * rs * kw1[1]); ko.w = pk2(kf[6] * rs * kw1[2], kf[7] * rs * kw1[3]);
;                 *(LAS v4u*)(Ks + key * 72 + 8 * oct) = ko;
;                 *(LAS v4u*)(Vs + key * 80 + 8 * oct) = vr[half][jj];
;             }
;         }
;         const int qi = 16 * w + l16;
;         const size_t qrow = (size_t)bl * SEQL + (size_t)(128 * n + qi) * d + r;
;         bf16x8 qreg[2];
;         {
;             float qf[2][8]; float ss = 0.f;
; #pragma unroll
;             for (int ks = 0; ks < 2; ++ks) {
;                 const v4u qq = qr[half][ks];
;                 qf[ks][0] = bflo(qq.x); qf[ks][1] = bfhi(qq.x); qf[ks][2] = bflo(qq.y); qf[ks][3] = bfhi(qq.y); qf[ks][4] = bflo(qq.z); qf[ks][5] = bfhi(qq.z); qf[ks][6] = bflo(qq.w); qf[ks][7] = bfhi(qq.w);
; #pragma unroll
;                 for (int e = 0; e < 8; ++e) ss += qf[ks][e] * qf[ks][e];
;             }
;             ss += __shfl_xor(ss, 16); ss += __shfl_xor(ss, 32);
;             const float rs = rsqrtf(ss * (1.f / 64.f) + EPS) * 0.125f;
; #pragma unroll
;             for (int ks = 0; ks < 2; ++ks) {
;                 const f32x4 w0 = *(const f32x4*)(qnw + gi * 64 + 32 * ks + 8 * g4), w1 = *(const f32x4*)(qnw + gi * 64 + 32 * ks + 8 * g4 + 4);
	v_pk_add_f32 v[92:93], v[92:93], v[96:97]
	s_nop 1
	v_mov_b32_dpp v97, v93 row_half_mirror row_mask:0xf bank_mask:0xf
	s_nop 1
	v_mov_b32_dpp v96, v92 row_half_mirror row_mask:0xf bank_mask:0xf
	v_lshlrev_b32_e32 v168, 16, v53
	v_and_b32_e32 v169, 0xffff0000, v53
	v_mov_b32_e32 v242, v238
	v_mov_b32_e32 v243, v180
	s_waitcnt lgkmcnt(0)
	v_pk_add_f32 v[92:93], v[92:93], v[96:97]
	v_mov_b32_e32 v241, v181
	v_pk_fma_f32 v[96:97], v[92:93], s[26:27], v[134:135] op_sel_hi:[1,0,0]
	v_pk_mul_f32 v[236:237], v[168:169], v[168:169]
	v_pk_add_f32 v[180:181], v[242:243], v[240:241]
	v_mov_b32_e32 v1, v97
	v_rsq_f32_e32 v1, v1
	v_lshlrev_b32_e32 v166, 16, v54
	v_and_b32_e32 v167, 0xffff0000, v54
	v_pk_mul_f32 v[234:235], v[166:167], v[166:167]
	s_nop 0
	v_mov_b32_e32 v100, v1
	v_mov_b32_e32 v1, v96
	v_rsq_f32_e32 v1, v1
	v_pk_mul_f32 v[94:95], v[100:101], v[94:95] op_sel_hi:[0,1]
	v_pk_mul_f32 v[2:3], v[100:101], v[2:3] op_sel_hi:[0,1]
	v_pk_mul_f32 v[92:93], v[100:101], v[102:103] op_sel_hi:[0,1]
	v_pk_mul_f32 v[98:99], v[100:101], v[98:99] op_sel_hi:[0,1]
	v_pk_mul_f32 v[94:95], v[84:85], v[94:95]
	v_pk_mul_f32 v[2:3], v[86:87], v[2:3]
	v_pk_mul_f32 v[92:93], v[88:89], v[92:93]
	v_pk_mul_f32 v[98:99], v[90:91], v[98:99]
	v_cvt_pk_bf16_f32 v94, v94, v95
	v_cvt_pk_bf16_f32 v95, v2, v3
	s_nop 0
	v_cvt_pk_bf16_f32 v92, v92, v93
	v_cvt_pk_bf16_f32 v93, v98, v99
	v_mov_b32_e32 v2, v1
	ds_write_b128 v229, v[92:95] offset:9216
	ds_write_b128 v231, v[16:19] offset:47104
	v_pk_mul_f32 v[92:93], v[2:3], v[156:157] op_sel_hi:[0,1]
	v_lshlrev_b32_e32 v156, 16, v41
	v_and_b32_e32 v157, 0xffff0000, v41
	v_pk_mul_f32 v[158:159], v[156:157], v[156:157]
	v_pk_mul_f32 v[94:95], v[2:3], v[152:153] op_sel_hi:[0,1]
	v_lshlrev_b32_e32 v152, 16, v42
	v_and_b32_e32 v153, 0xffff0000, v42
	v_pk_mov_b32 v[238:239], v[238:239], v[158:159] op_sel:[1,0]
	v_pk_mul_f32 v[92:93], v[88:89], v[92:93]
	v_pk_mul_f32 v[94:95], v[90:91], v[94:95]
	v_pk_mul_f32 v[154:155], v[152:153], v[152:153]
	v_pk_add_f32 v[180:181], v[238:239], v[180:181]
	v_mov_b32_e32 v158, v236
	v_cvt_pk_bf16_f32 v92, v92, v93
	v_cvt_pk_bf16_f32 v93, v94, v95
	v_pk_mul_f32 v[94:95], v[2:3], v[136:137] op_sel_hi:[0,1]
	v_lshlrev_b32_e32 v136, 16, v43
	v_and_b32_e32 v137, 0xffff0000, v43
	v_pk_add_f32 v[158:159], v[158:159], v[180:181]
	v_pk_mov_b32 v[180:181], v[236:237], v[154:155] op_sel:[1,0]
	v_pk_mul_f32 v[150:151], v[136:137], v[136:137]
	v_lshlrev_b32_e32 v164, 16, v55
	v_and_b32_e32 v165, 0xffff0000, v55
	v_pk_add_f32 v[158:159], v[180:181], v[158:159]
	v_mov_b32_e32 v154, v234
	v_pk_mul_f32 v[232:233], v[164:165], v[164:165]
	v_pk_add_f32 v[154:155], v[154:155], v[158:159]
	v_pk_mov_b32 v[158:159], v[234:235], v[150:151] op_sel:[1,0]
	v_mov_b32_e32 v150, v232
	v_pk_add_f32 v[154:155], v[158:159], v[154:155]
	v_pk_mul_f32 v[2:3], v[2:3], v[106:107] op_sel_hi:[0,1]
	v_pk_add_f32 v[150:151], v[150:151], v[154:155]
	s_nop 1
	v_mov_b32_dpp v155, v151 quad_perm:[1,0,3,2] row_mask:0xf bank_mask:0xf
	v_mov_b32_e32 v154, v233
	v_pk_mul_f32 v[94:95], v[84:85], v[94:95]
	v_pk_mul_f32 v[2:3], v[86:87], v[2:3]
	s_ashr_i32 s0, s21, 4
	s_waitcnt lgkmcnt(0)
	v_pk_add_f32 v[150:151], v[154:155], v[150:151]
	s_nop 1
	v_mov_b32_dpp v155, v151 quad_perm:[2,3,0,1] row_mask:0xf bank_mask:0xf
	v_mov_b32_e32 v154, v150
	s_nop 1
	v_permlane16_swap_b32_e32 v154, v150
	s_lshr_b32 s54, s20, s3
	v_cvt_pk_bf16_f32 v94, v94, v95
	v_cvt_pk_bf16_f32 v95, v2, v3
	s_ashr_i32 s1, s0, 31
	s_waitcnt lgkmcnt(0)
	v_pk_add_f32 v[150:151], v[150:151], v[154:155]
	s_nop 1
	v_mov_b32_dpp v155, v151 row_half_mirror row_mask:0xf bank_mask:0xf
	v_mov_b32_e32 v154, v150
	s_nop 1
	v_permlane32_swap_b32_e32 v154, v150
	v_lshl_add_u32 v2, s54, 7, v147
	s_and_b32 s53, s21, 15
	s_lshl_b64 s[20:21], s[0:1], 11
	v_ashrrev_i32_e32 v3, 31, v2
	s_waitcnt lgkmcnt(0)
	v_pk_add_f32 v[150:151], v[150:151], v[154:155]
	s_or_b32 s20, s20, s22
	v_pk_fma_f32 v[180:181], v[150:151], s[26:27], v[134:135] op_sel_hi:[1,0,0]
	v_lshlrev_b64 v[2:3], s3, v[2:3]
	ds_write_b128 v229, v[92:95] offset:18432
	ds_write_b128 v231, v[24:27] offset:57344
	v_mov_b32_e32 v1, v181
	v_rsq_f32_e32 v1, v1
	v_lshl_add_u64 v[96:97], v[114:115], 0, s[24:25]
	s_lshl_b32 s26, s53, 7
	global_load_dwordx4 v[100:103], v[96:97], off offset:16
	global_load_dwordx4 v[104:107], v[96:97], off
	global_load_dwordx4 v[92:95], v[96:97], off offset:144
	s_nop 0
	global_load_dwordx4 v[96:99], v[96:97], off offset:128
	s_nop 0
	v_mov_b32_e32 v134, v1
	v_pk_mul_f32 v[150:151], v[134:135], v[162:163] op_sel_hi:[0,1]
	v_pk_mul_f32 v[88:89], v[88:89], v[150:151]
	v_pk_mul_f32 v[150:151], v[134:135], v[156:157] op_sel_hi:[0,1]
	v_pk_mul_f32 v[90:91], v[90:91], v[150:151]
	v_cvt_pk_bf16_f32 v88, v88, v89
	v_cvt_pk_bf16_f32 v89, v90, v91
	v_pk_mul_f32 v[90:91], v[134:135], v[152:153] op_sel_hi:[0,1]
	v_pk_mul_f32 v[84:85], v[84:85], v[90:91]
	v_cmp_gt_f32_e64 s[0:1], s33, v180
	v_cvt_pk_bf16_f32 v90, v84, v85
	v_pk_mul_f32 v[84:85], v[134:135], v[136:137] op_sel_hi:[0,1]
	v_lshl_add_u64 v[136:137], s[20:21], 0, v[2:3]
	v_lshlrev_b64 v[162:163], 11, v[136:137]
	v_pk_mul_f32 v[84:85], v[86:87], v[84:85]
	v_lshl_add_u64 v[2:3], s[28:29], 0, v[162:163]
	v_cvt_pk_bf16_f32 v91, v84, v85
	v_lshl_add_u64 v[2:3], v[2:3], 0, s[26:27]
	v_lshlrev_b32_e32 v134, 1, v112
	v_mov_b32_e32 v135, v0
	ds_write_b128 v229, v[88:91] offset:27648
	ds_write_b128 v230, v[44:47] offset:57344
	v_lshl_add_u64 v[2:3], v[2:3], 0, v[134:135]
	global_load_dwordx4 v[88:91], v[2:3], off nt
	global_load_dwordx4 v[84:87], v[2:3], off offset:64 nt
	v_readlane_b32 s20, v252, 59
	s_add_i32 s52, s51, s20
	s_waitcnt lgkmcnt(0)
	s_barrier
; __device__ __forceinline__ void attn_phase(LAS unsigned char* lds, const bf16* PROJ, const bf16* Ygate, bf16* OG0, bf16* OG1, bf16* OG2, float* LSE, const float* qnw, const float* knw, int bx, int G) {
;     ...
;         if (t + 2 * G < 3072) AT_LOAD(t + 2 * G, half);
	s_cmpk_gt_i32 s52, 0xbff
	s_cselect_b64 s[24:25], -1, 0
	s_and_b64 vcc, exec, s[24:25]
	s_cbranch_vccnz .LBB0_279
	s_ashr_i32 s21, s52, 4
	s_mul_hi_i32 s22, s21, 0x55555556
	s_lshr_b32 s23, s22, 31
	s_add_i32 s22, s22, s23
	s_mul_i32 s22, s22, 3
	s_sub_i32 s21, s21, s22
	s_mul_hi_i32 s22, s52, 0x2aaaaaab
	s_lshr_b32 s23, s22, 31
	s_ashr_i32 s22, s22, 3
	s_lshl_b32 s26, s21, 1
	s_and_b32 s20, s52, 15
	s_add_i32 s23, s22, s23
	s_lshl_b32 s30, -1, s26
	s_andn2_b32 s30, s20, s30
	s_lshr_b32 s31, s20, s26
	s_lshl_b32 s20, s23, 6
	s_ashr_i32 s22, s23, 4
	s_mulk_i32 s21, 0xc00
	s_and_b32 s20, s20, 0x3c0
	s_or_b32 s20, s21, s20
	s_ashr_i32 s23, s22, 31
	s_lshl_b64 s[22:23], s[22:23], 11
	s_ashr_i32 s21, s20, 31
	s_lshl_b32 s55, s31, 7
	s_or_b32 s22, s22, s30
	s_lshl_b64 s[30:31], s[20:21], 1
	v_mov_b32_e32 v6, v0
	v_mov_b32_e32 v7, v0
	v_add_u32_e32 v48, s55, v182
	s_add_u32 s38, s34, s30
	v_mov_b32_e32 v4, v0
	v_mov_b32_e32 v5, v0
	v_mov_b64_e32 v[10:11], v[6:7]
	v_mov_b64_e32 v[14:15], v[6:7]
	s_addc_u32 s39, s35, s31
	v_cmp_lt_i32_e32 vcc, -1, v48
	v_mov_b64_e32 v[8:9], v[4:5]
	v_mov_b64_e32 v[12:13], v[4:5]
	s_and_saveexec_b64 s[30:31], vcc
	s_cbranch_execz .LBB0_272
	v_mov_b32_e32 v49, v0
	v_lshlrev_b64 v[2:3], s26, v[48:49]
	v_lshl_add_u64 v[2:3], v[2:3], 0, s[22:23]
	v_mov_b64_e32 v[8:9], s[38:39]
	s_movk_i32 s80, 0x4800
	v_mad_u64_u32 v[8:9], vcc, v2, s80, v[8:9]
	v_mov_b32_e32 v2, v9
	v_mad_u64_u32 v[2:3], vcc, v3, s80, v[2:3]
	v_mov_b32_e32 v9, v2
	v_lshlrev_b32_e32 v2, 1, v108
	v_mov_b32_e32 v3, v0
	v_lshl_add_u64 v[2:3], v[8:9], 0, v[2:3]
	v_add_co_u32_e32 v12, vcc, 0x1000, v2
	s_nop 1
	v_addc_co_u32_e32 v13, vcc, 0, v3, vcc
	global_load_dwordx4 v[8:11], v[2:3], off offset:2048
	s_nop 0
	global_load_dwordx4 v[12:15], v[12:13], off

.LBB0_278:
	s_or_b64 exec, exec, s[30:31]
	v_add_u32_e32 v2, s55, v147
	v_ashrrev_i32_e32 v3, 31, v2
	v_lshlrev_b64 v[2:3], s26, v[2:3]
	v_lshl_add_u64 v[2:3], v[2:3], 0, s[22:23]
	v_mov_b64_e32 v[48:49], s[34:35]
	s_movk_i32 s26, 0x4800
	v_mad_u64_u32 v[48:49], s[22:23], v2, s26, v[48:49]
	v_mov_b32_e32 v2, v49
	v_mad_u64_u32 v[2:3], s[22:23], v3, s26, v[2:3]
	v_mov_b32_e32 v49, v2
	v_lshl_add_u64 v[2:3], s[20:21], 1, v[48:49]
	v_mov_b32_e32 v135, v0
	v_lshl_add_u64 v[2:3], v[2:3], 0, v[134:135]
	global_load_dwordx4 v[48:51], v[2:3], off nt
	global_load_dwordx4 v[52:55], v[2:3], off offset:64 nt

; #define LAS __attribute__((address_space(3)))
; __device__ __forceinline__ float bflo(unsigned u) { return __uint_as_float(u << 16); }
; __device__ __forceinline__ float bfhi(unsigned u) { return __uint_as_float(u & 0xffff0000u); }
; __device__ __forceinline__ unsigned pk2(float lo, float hi) { f32x2_t v = {lo, hi}; bf16x2_t b = __builtin_convertvector(v, bf16x2_t); return __builtin_bit_cast(unsigned, b); }
; __device__ __forceinline__ void attn_phase(LAS unsigned char* lds, const bf16* PROJ, const bf16* Ygate, bf16* OG0, bf16* OG1, bf16* OG2, float* LSE, const float* qnw, const float* knw, int bx, int G) {
;     ...
;         const int sub = t & 15, gi = (t >> 4) % 3, bh = t / 48, h = bh & 15, bl = bh >> 4;
;         const int sh = 2 * gi, d = 1 << sh, r = sub & (d - 1), n = sub >> sh;
;         const float ad = exp2f(-8.f * (float)(gi * 16 + h + 1) / 48.f) * (float)d;
;         bf16* OG = gi == 0 ? OG0 : (gi == 1 ? OG1 : OG2);
;         {
;             const f32x4 kw0 = *(const f32x4*)(knw + gi * 64 + 8 * oct), kw1 = *(const f32x4*)(knw + gi * 64 + 8 * oct + 4);
; #pragma unroll
;             for (int jj = 0; jj < 4; ++jj) {
;                 const int key = (tid >> 3) + 64 * jj; const v4u kq = kr[half][jj];
;                 float kf[8] = {bflo(kq.x), bfhi(kq.x), bflo(kq.y), bfhi(kq.y), bflo(kq.z), bfhi(kq.z), bflo(kq.w), bfhi(kq.w)};
;                 float ss = 0.f;
; #pragma unroll
;                 for (int e = 0; e < 8; ++e) ss += kf[e] * kf[e];
;                 ss += __shfl_xor(ss, 1); ss += __shfl_xor(ss, 2); ss += __shfl_xor(ss, 4);
;                 const float rs = rsqrtf(ss * (1.f / 64.f) + EPS);
;                 v4u ko; ko.x = pk2(kf[0] * rs * kw0[0], kf[1] * rs * kw0[1]); ko.y = pk2(kf[2] * rs * kw0[2], kf[3] * rs * kw0[3]);
;                 ko.z = pk2(kf[4] * rs * kw1[0], kf[5] * rs * kw1[1]); ko.w = pk2(kf[6] * rs * kw1[2], kf[7] * rs * kw1[3]);
;                 *(LAS v4u*)(Ks + key * 72 + 8 * oct) = ko;
;                 *(LAS v4u*)(Vs + key * 80 + 8 * oct) = vr[half][jj];
;             }
.LBB0_308:
	s_or_b64 exec, exec, s[0:1]
	s_waitcnt lgkmcnt(0)
	s_barrier
	s_add_i32 s0, s84, s51
	s_cmpk_gt_i32 s0, 0xbff
	s_cbranch_scc1 .LBB0_268
	s_ashr_i32 s1, s0, 4
	s_mul_hi_i32 s2, s1, 0x55555556
	s_lshr_b32 s3, s2, 31
	s_add_i32 s2, s2, s3
	s_mul_i32 s2, s2, 3
	s_sub_i32 s2, s1, s2
	s_and_b32 s22, s0, 15
	s_mul_hi_i32 s0, s0, 0x2aaaaaab
	s_lshl_b32 s3, s2, 1
	s_lshr_b32 s1, s0, 31
	s_ashr_i32 s23, s0, 3
	s_bfm_b32 s0, s3, 0
	s_and_b32 s26, s0, s22
	s_lshl_b32 s0, s2, 6
	s_add_i32 s23, s23, s1
	s_ashr_i32 s1, s0, 31
	s_lshl_b64 s[20:21], s[0:1], 2
	v_lshl_add_u64 v[2:3], v[110:111], 0, s[20:21]
	global_load_dwordx4 v[84:87], v[2:3], off offset:16
	global_load_dwordx4 v[88:91], v[2:3], off
	v_lshlrev_b32_e32 v102, 16, v32
	v_and_b32_e32 v103, 0xffff0000, v32
	v_lshlrev_b32_e32 v98, 16, v33
	v_and_b32_e32 v99, 0xffff0000, v33
	v_pk_mul_f32 v[104:105], v[102:103], v[102:103]
	v_pk_mul_f32 v[100:101], v[98:99], v[98:99]
	v_add_f32_e32 v1, v104, v105
	v_lshlrev_b32_e32 v94, 16, v34
	v_and_b32_e32 v95, 0xffff0000, v34
	v_add_f32_e32 v1, v100, v1
	v_pk_mul_f32 v[96:97], v[94:95], v[94:95]
	v_add_f32_e32 v1, v101, v1
	v_lshlrev_b32_e32 v2, 16, v35
	v_and_b32_e32 v3, 0xffff0000, v35
	v_add_f32_e32 v1, v96, v1
	v_pk_mul_f32 v[92:93], v[2:3], v[2:3]
	v_add_f32_e32 v1, v97, v1
	v_add_f32_e32 v1, v92, v1
	v_add_f32_e32 v1, v93, v1
	s_nop 1
	v_mov_b32_dpp v92, v1 quad_perm:[1,0,3,2] row_mask:0xf bank_mask:0xf
	v_lshlrev_b32_e32 v158, 16, v60
	v_and_b32_e32 v159, 0xffff0000, v60
	v_lshlrev_b32_e32 v154, 16, v61
	v_and_b32_e32 v155, 0xffff0000, v61
	s_waitcnt lgkmcnt(0)
	v_add_f32_e32 v1, v1, v92
	s_nop 1
	v_mov_b32_dpp v92, v1 quad_perm:[2,3,0,1] row_mask:0xf bank_mask:0xf
	v_pk_mul_f32 v[162:163], v[158:159], v[158:159]
	v_pk_mul_f32 v[156:157], v[154:155], v[154:155]
	v_mov_b32_e32 v164, v162
	v_lshlrev_b32_e32 v150, 16, v62
	s_waitcnt lgkmcnt(0)
	v_add_f32_e32 v1, v1, v92
	s_nop 1
	v_mov_b32_dpp v92, v1 row_half_mirror row_mask:0xf bank_mask:0xf
	v_and_b32_e32 v151, 0xffff0000, v62
	v_mov_b32_e32 v162, v156
	v_pk_mul_f32 v[152:153], v[150:151], v[150:151]
	v_lshlrev_b32_e32 v106, 16, v63
	s_waitcnt lgkmcnt(0)
	v_add_f32_e32 v1, v1, v92
	v_fmamk_f32 v1, v1, 0x3c800000, v139
	v_and_b32_e32 v107, 0xffff0000, v63
	v_rsq_f32_e32 v1, v1
	v_pk_mul_f32 v[136:137], v[106:107], v[106:107]
	s_mov_b32 s0, 0x358637bd
	s_mov_b32 s38, 0x3c800000
	s_nop 0
	v_mov_b32_e32 v96, v1
	v_pk_mul_f32 v[92:93], v[96:97], v[102:103] op_sel_hi:[0,1]
	v_pk_mul_f32 v[98:99], v[96:97], v[98:99] op_sel_hi:[0,1]
	v_pk_mul_f32 v[94:95], v[96:97], v[94:95] op_sel_hi:[0,1]
	v_pk_mul_f32 v[2:3], v[96:97], v[2:3] op_sel_hi:[0,1]
	v_lshlrev_b32_e32 v102, 16, v28
	v_and_b32_e32 v103, 0xffff0000, v28
	v_pk_mul_f32 v[104:105], v[102:103], v[102:103]
	v_and_b32_e32 v179, 0xffff0000, v76
	v_mov_b32_e32 v165, v104
	v_mov_b32_e32 v104, v163
	v_pk_add_f32 v[104:105], v[164:165], v[104:105]
	v_lshlrev_b32_e32 v178, 16, v76
	v_mul_f32_e32 v242, v179, v179
	v_lshlrev_b32_e32 v176, 16, v77
	v_and_b32_e32 v177, 0xffff0000, v77
	v_pk_fma_f32 v[242:243], v[178:179], v[178:179], v[242:243] op_sel_hi:[1,1,0]
	v_mul_f32_e32 v244, v177, v177
	v_pk_fma_f32 v[242:243], v[176:177], v[176:177], v[242:243]
	v_lshlrev_b32_e32 v174, 16, v78
	v_and_b32_e32 v175, 0xffff0000, v78
	v_pk_add_f32 v[242:243], v[244:245], v[242:243] op_sel_hi:[0,1]
	v_pk_fma_f32 v[242:243], v[174:175], v[174:175], v[242:243]
	v_mul_f32_e32 v244, v175, v175
	v_lshlrev_b32_e32 v172, 16, v79
	v_and_b32_e32 v173, 0xffff0000, v79
	v_pk_add_f32 v[242:243], v[244:245], v[242:243] op_sel_hi:[0,1]
	v_lshlrev_b32_e32 v232, 16, v68
	v_and_b32_e32 v233, 0xffff0000, v68
	v_lshlrev_b32_e32 v170, 16, v80
	v_and_b32_e32 v171, 0xffff0000, v80
	s_waitcnt vmcnt(1)
	v_pk_mul_f32 v[94:95], v[84:85], v[94:95]
	s_waitcnt vmcnt(0)
	v_pk_mul_f32 v[92:93], v[88:89], v[92:93]
	v_pk_mul_f32 v[98:99], v[90:91], v[98:99]
	v_cvt_pk_bf16_f32 v92, v92, v93
	v_cvt_pk_bf16_f32 v93, v98, v99
	v_pk_mul_f32 v[2:3], v[86:87], v[2:3]
	v_lshlrev_b32_e32 v98, 16, v29
	v_and_b32_e32 v99, 0xffff0000, v29
	v_cvt_pk_bf16_f32 v94, v94, v95
	v_cvt_pk_bf16_f32 v95, v2, v3
	v_pk_mul_f32 v[100:101], v[98:99], v[98:99]
	ds_write_b128 v229, v[92:95]
	ds_write_b128 v231, v[36:39] offset:36864
	v_lshlrev_b32_e32 v94, 16, v30
	v_and_b32_e32 v95, 0xffff0000, v30
	v_mov_b32_e32 v163, v100
	v_pk_mul_f32 v[96:97], v[94:95], v[94:95]
	v_pk_add_f32 v[104:105], v[162:163], v[104:105]
	v_mov_b32_e32 v100, v157
	v_lshlrev_b32_e32 v2, 16, v31
	v_and_b32_e32 v3, 0xffff0000, v31
	v_pk_add_f32 v[100:101], v[100:101], v[104:105]
	v_mov_b32_e32 v104, v152
	v_mov_b32_e32 v105, v96
	v_pk_mul_f32 v[92:93], v[2:3], v[2:3]
	v_pk_add_f32 v[100:101], v[104:105], v[100:101]
	v_mov_b32_e32 v96, v153
	v_pk_add_f32 v[96:97], v[96:97], v[100:101]
	v_mov_b32_e32 v100, v136
	v_mov_b32_e32 v101, v92
	v_pk_add_f32 v[96:97], v[100:101], v[96:97]
	v_mov_b32_e32 v92, v137
	v_pk_add_f32 v[92:93], v[92:93], v[96:97]
	s_nop 1
	v_mov_b32_dpp v97, v93 quad_perm:[1,0,3,2] row_mask:0xf bank_mask:0xf
	s_nop 1
	v_mov_b32_dpp v96, v92 quad_perm:[1,0,3,2] row_mask:0xf bank_mask:0xf
	v_mov_b64_e32 v[136:137], s[0:1]
	v_pk_fma_f32 v[242:243], v[172:173], v[172:173], v[242:243]
	v_mul_f32_e32 v244, v173, v173
	v_pk_mul_f32 v[180:181], v[232:233], v[232:233]
	s_waitcnt lgkmcnt(0)
	v_pk_add_f32 v[92:93], v[92:93], v[96:97]
	s_nop 1
	v_mov_b32_dpp v97, v93 quad_perm:[2,3,0,1] row_mask:0xf bank_mask:0xf
	s_nop 1
	v_mov_b32_dpp v96, v92 quad_perm:[2,3,0,1] row_mask:0xf bank_mask:0xf
	v_pk_mul_f32 v[240:241], v[170:171], v[170:171]
	v_pk_add_f32 v[242:243], v[244:245], v[242:243] op_sel_hi:[0,1]
	v_lshlrev_b32_e32 v168, 16, v81
	v_and_b32_e32 v169, 0xffff0000, v81
	s_waitcnt lgkmcnt(0)
; #define LAS __attribute__((address_space(3)))
; __device__ __forceinline__ void attn_phase(LAS unsigned char* lds, const bf16* PROJ, const bf16* Ygate, bf16* OG0, bf16* OG1, bf16* OG2, float* LSE, const float* qnw, const float* knw, int bx, int G) {
;     ...
;             const f32x4 kw0 = *(const f32x4*)(knw + gi * 64 + 8 * oct), kw1 = *(const f32x4*)(knw + gi * 64 + 8 * oct + 4);
; #pragma unroll
;             for (int jj = 0; jj < 4; ++jj) {
;                 const int key = (tid >> 3) + 64 * jj; const v4u kq = kr[half][jj];
;                 float kf[8] = {bflo(kq.x), bfhi(kq.x), bflo(kq.y), bfhi(kq.y), bflo(kq.z), bfhi(kq.z), bflo(kq.w), bfhi(kq.w)};
;                 float ss = 0.f;
; #pragma unroll
;                 for (int e = 0; e < 8; ++e) ss += kf[e] * kf[e];
;                 ss += __shfl_xor(ss, 1); ss += __shfl_xor(ss, 2); ss += __shfl_xor(ss, 4);
;                 const float rs = rsqrtf(ss * (1.f / 64.f) + EPS);
;                 v4u ko; ko.x = pk2(kf[0] * rs * kw0[0], kf[1] * rs * kw0[1]); ko.y = pk2(kf[2] * rs * kw0[2], kf[3] * rs * kw0[3]);
;                 ko.z = pk2(kf[4] * rs * kw1[0], kf[5] * rs * kw1[1]); ko.w = pk2(kf[6] * rs * kw1[2], kf[7] * rs * kw1[3]);
;                 *(LAS v4u*)(Ks + key * 72 + 8 * oct) = ko;
;                 *(LAS v4u*)(Vs + key * 80 + 8 * oct) = vr[half][jj];
;             }
;         }
;         const int qi = 16 * w + l16;
;         const size_t qrow = (size_t)bl * SEQL + (size_t)(128 * n + qi) * d + r;
;         bf16x8 qreg[2];
;         {
;             float qf[2][8]; float ss = 0.f;
; #pragma unroll
;             for (int ks = 0; ks < 2; ++ks) {
;                 const v4u qq = qr[half][ks];
;                 qf[ks][0] = bflo(qq.x); qf[ks][1] = bfhi(qq.x); qf[ks][2] = bflo(qq.y); qf[ks][3] = bfhi(qq.y); qf[ks][4] = bflo(qq.z); qf[ks][5] = bfhi(qq.z); qf[ks][6] = bflo(qq.w); qf[ks][7] = bfhi(qq.w);
; #pragma unroll
;                 for (int e = 0; e < 8; ++e) ss += qf[ks][e] * qf[ks][e];
;             }
;             ss += __shfl_xor(ss, 16); ss += __shfl_xor(ss, 32);
;             const float rs = rsqrtf(ss * (1.f / 64.f) + EPS) * 0.125f;
; #pragma unroll
;             for (int ks = 0; ks < 2; ++ks) {
;                 const f32x4 w0 = *(const f32x4*)(qnw + gi * 64 + 32 * ks + 8 * g4), w1 = *(const f32x4*)(qnw + gi * 64 + 32 * ks + 8 * g4 + 4);
	v_pk_add_f32 v[92:93], v[92:93], v[96:97]
	s_nop 1
	v_mov_b32_dpp v97, v93 row_half_mirror row_mask:0xf bank_mask:0xf
	s_nop 1
	v_mov_b32_dpp v96, v92 row_half_mirror row_mask:0xf bank_mask:0xf
	v_mov_b32_e32 v244, v240
	v_mov_b32_e32 v245, v180
	v_mov_b32_e32 v243, v181
	v_pk_mul_f32 v[238:239], v[168:169], v[168:169]
	s_waitcnt lgkmcnt(0)
	v_pk_add_f32 v[92:93], v[92:93], v[96:97]
	v_pk_add_f32 v[180:181], v[244:245], v[242:243]
	v_pk_fma_f32 v[96:97], v[92:93], s[38:39], v[136:137] op_sel_hi:[1,0,0]
	v_lshlrev_b32_e32 v166, 16, v82
	v_and_b32_e32 v167, 0xffff0000, v82
	v_mov_b32_e32 v1, v97
	v_rsq_f32_e32 v1, v1
	v_pk_mul_f32 v[236:237], v[166:167], v[166:167]
	v_lshlrev_b32_e32 v164, 16, v83
	v_and_b32_e32 v165, 0xffff0000, v83
	s_nop 0
	v_mov_b32_e32 v100, v1
	v_mov_b32_e32 v1, v96
	v_rsq_f32_e32 v1, v1
	v_pk_mul_f32 v[94:95], v[100:101], v[94:95] op_sel_hi:[0,1]
	v_pk_mul_f32 v[2:3], v[100:101], v[2:3] op_sel_hi:[0,1]
	v_pk_mul_f32 v[92:93], v[100:101], v[102:103] op_sel_hi:[0,1]
	v_pk_mul_f32 v[98:99], v[100:101], v[98:99] op_sel_hi:[0,1]
	v_pk_mul_f32 v[94:95], v[84:85], v[94:95]
	v_pk_mul_f32 v[2:3], v[86:87], v[2:3]
	v_pk_mul_f32 v[92:93], v[88:89], v[92:93]
	v_pk_mul_f32 v[98:99], v[90:91], v[98:99]
	v_cvt_pk_bf16_f32 v94, v94, v95
	v_cvt_pk_bf16_f32 v95, v2, v3
	s_nop 0
	v_cvt_pk_bf16_f32 v92, v92, v93
	v_cvt_pk_bf16_f32 v93, v98, v99
	v_mov_b32_e32 v2, v1
	ds_write_b128 v229, v[92:95] offset:9216
	ds_write_b128 v231, v[56:59] offset:47104
	v_pk_mul_f32 v[92:93], v[2:3], v[158:159] op_sel_hi:[0,1]
	v_lshlrev_b32_e32 v158, 16, v69
	v_and_b32_e32 v159, 0xffff0000, v69
	v_pk_mul_f32 v[162:163], v[158:159], v[158:159]
	v_pk_mul_f32 v[94:95], v[2:3], v[154:155] op_sel_hi:[0,1]
	v_lshlrev_b32_e32 v154, 16, v70
	v_and_b32_e32 v155, 0xffff0000, v70
	v_pk_mov_b32 v[240:241], v[240:241], v[162:163] op_sel:[1,0]
	v_pk_mul_f32 v[92:93], v[88:89], v[92:93]
	v_pk_mul_f32 v[94:95], v[90:91], v[94:95]
	v_pk_mul_f32 v[156:157], v[154:155], v[154:155]
	v_pk_add_f32 v[180:181], v[240:241], v[180:181]
	v_mov_b32_e32 v162, v238
	v_cvt_pk_bf16_f32 v92, v92, v93
	v_cvt_pk_bf16_f32 v93, v94, v95
	v_pk_mul_f32 v[94:95], v[2:3], v[150:151] op_sel_hi:[0,1]
	v_lshlrev_b32_e32 v150, 16, v71
	v_and_b32_e32 v151, 0xffff0000, v71
	v_pk_add_f32 v[162:163], v[162:163], v[180:181]
	v_pk_mov_b32 v[180:181], v[238:239], v[156:157] op_sel:[1,0]
	v_pk_mul_f32 v[152:153], v[150:151], v[150:151]
	v_pk_add_f32 v[162:163], v[180:181], v[162:163]
	v_mov_b32_e32 v156, v236
	v_pk_mul_f32 v[234:235], v[164:165], v[164:165]
	v_pk_add_f32 v[156:157], v[156:157], v[162:163]
	v_pk_mov_b32 v[162:163], v[236:237], v[152:153] op_sel:[1,0]
	v_mov_b32_e32 v152, v234
	v_pk_add_f32 v[156:157], v[162:163], v[156:157]
	v_pk_mul_f32 v[2:3], v[2:3], v[106:107] op_sel_hi:[0,1]
	v_pk_add_f32 v[152:153], v[152:153], v[156:157]
	s_nop 1
	v_mov_b32_dpp v157, v153 quad_perm:[1,0,3,2] row_mask:0xf bank_mask:0xf
	v_mov_b32_e32 v156, v235
	v_pk_mul_f32 v[94:95], v[84:85], v[94:95]
	v_pk_mul_f32 v[2:3], v[86:87], v[2:3]
	s_ashr_i32 s0, s23, 4
	s_waitcnt lgkmcnt(0)
	v_pk_add_f32 v[152:153], v[156:157], v[152:153]
	s_nop 1
	v_mov_b32_dpp v157, v153 quad_perm:[2,3,0,1] row_mask:0xf bank_mask:0xf
	v_mov_b32_e32 v156, v152
	s_nop 1
	v_permlane16_swap_b32_e32 v156, v152
	s_lshr_b32 s54, s22, s3
	v_cvt_pk_bf16_f32 v94, v94, v95
	v_cvt_pk_bf16_f32 v95, v2, v3
	s_ashr_i32 s1, s0, 31
	s_waitcnt lgkmcnt(0)
	v_pk_add_f32 v[152:153], v[152:153], v[156:157]
	s_nop 1
	v_mov_b32_dpp v157, v153 row_half_mirror row_mask:0xf bank_mask:0xf
	v_mov_b32_e32 v156, v152
	s_nop 1
	v_permlane32_swap_b32_e32 v156, v152
	v_lshl_add_u32 v2, s54, 7, v147
	s_and_b32 s53, s23, 15
	s_lshl_b64 s[22:23], s[0:1], 11
	v_ashrrev_i32_e32 v3, 31, v2
	s_waitcnt lgkmcnt(0)
	v_pk_add_f32 v[152:153], v[152:153], v[156:157]
	s_or_b32 s22, s22, s26
	v_pk_fma_f32 v[180:181], v[152:153], s[38:39], v[136:137] op_sel_hi:[1,0,0]
	v_lshlrev_b64 v[2:3], s3, v[2:3]
	ds_write_b128 v229, v[92:95] offset:18432
	ds_write_b128 v231, v[64:67] offset:57344
	v_mov_b32_e32 v1, v181
	v_rsq_f32_e32 v1, v1
	v_lshl_add_u64 v[96:97], v[114:115], 0, s[20:21]
	s_lshl_b32 s26, s53, 7
	global_load_dwordx4 v[100:103], v[96:97], off offset:16
	global_load_dwordx4 v[104:107], v[96:97], off
	global_load_dwordx4 v[92:95], v[96:97], off offset:144
	s_nop 0
	global_load_dwordx4 v[96:99], v[96:97], off offset:128
	s_nop 0
	v_mov_b32_e32 v136, v1
	v_pk_mul_f32 v[152:153], v[136:137], v[232:233] op_sel_hi:[0,1]
	v_pk_mul_f32 v[88:89], v[88:89], v[152:153]
	v_pk_mul_f32 v[152:153], v[136:137], v[158:159] op_sel_hi:[0,1]
	v_pk_mul_f32 v[90:91], v[90:91], v[152:153]
	v_cvt_pk_bf16_f32 v88, v88, v89
	v_cvt_pk_bf16_f32 v89, v90, v91
	v_pk_mul_f32 v[90:91], v[136:137], v[154:155] op_sel_hi:[0,1]
	v_pk_mul_f32 v[84:85], v[84:85], v[90:91]
	v_mov_b32_e32 v135, v0
	v_cvt_pk_bf16_f32 v90, v84, v85
	v_pk_mul_f32 v[84:85], v[136:137], v[150:151] op_sel_hi:[0,1]
	v_lshl_add_u64 v[136:137], s[22:23], 0, v[2:3]
	v_lshlrev_b64 v[162:163], 11, v[136:137]
	v_pk_mul_f32 v[84:85], v[86:87], v[84:85]
	v_lshl_add_u64 v[2:3], s[28:29], 0, v[162:163]
	v_cvt_pk_bf16_f32 v91, v84, v85
	v_lshl_add_u64 v[2:3], v[2:3], 0, s[26:27]
	ds_write_b128 v229, v[88:91] offset:27648
	ds_write_b128 v230, v[72:75] offset:57344
	v_lshl_add_u64 v[2:3], v[2:3], 0, v[134:135]
	global_load_dwordx4 v[88:91], v[2:3], off nt
	global_load_dwordx4 v[84:87], v[2:3], off offset:64 nt
	s_waitcnt lgkmcnt(0)
	s_barrier
; __device__ __forceinline__ void attn_phase(LAS unsigned char* lds, const bf16* PROJ, const bf16* Ygate, bf16* OG0, bf16* OG1, bf16* OG2, float* LSE, const float* qnw, const float* knw, int bx, int G) {
;     ...
;         if (t + 2 * G < 3072) AT_LOAD(t + 2 * G, half);
	s_mul_i32 s20, s84, 3
	s_add_i32 s20, s20, s51
	v_cmp_gt_f32_e64 s[0:1], s33, v180
	s_cmpk_gt_i32 s20, 0xbff
	s_cbranch_scc1 .LBB0_319
	s_ashr_i32 s22, s20, 4
	s_mul_hi_i32 s23, s22, 0x55555556
	s_lshr_b32 s26, s23, 31
	s_add_i32 s23, s23, s26
	s_and_b32 s21, s20, 15
	s_mul_i32 s23, s23, 3
	s_mul_hi_i32 s20, s20, 0x2aaaaaab
	s_sub_i32 s23, s22, s23
	s_lshr_b32 s22, s20, 31
	s_ashr_i32 s20, s20, 3
	s_add_i32 s20, s20, s22
	s_ashr_i32 s22, s20, 4
	s_lshl_b32 s26, s23, 1
	s_lshl_b32 s20, s20, 6
	s_lshl_b32 s30, -1, s26
	s_mulk_i32 s23, 0xc00
	s_and_b32 s20, s20, 0x3c0
	s_andn2_b32 s30, s21, s30
	s_lshr_b32 s21, s21, s26
	s_or_b32 s20, s23, s20
	s_ashr_i32 s23, s22, 31
	s_lshl_b32 s51, s21, 7
	s_lshl_b64 s[22:23], s[22:23], 11
	s_ashr_i32 s21, s20, 31
	s_or_b32 s22, s22, s30
	s_lshl_b64 s[30:31], s[20:21], 1
	v_mov_b32_e32 v30, v0
	v_mov_b32_e32 v31, v0
	v_add_u32_e32 v76, s51, v182
	s_add_u32 s38, s34, s30
	v_mov_b32_e32 v28, v0
	v_mov_b32_e32 v29, v0
	v_mov_b64_e32 v[34:35], v[30:31]
	v_mov_b64_e32 v[38:39], v[30:31]
	s_addc_u32 s39, s35, s31
	v_cmp_lt_i32_e32 vcc, -1, v76
	v_lshlrev_b32_e32 v78, 1, v108
	v_mov_b64_e32 v[32:33], v[28:29]
	v_mov_b64_e32 v[36:37], v[28:29]
	s_and_saveexec_b64 s[30:31], vcc
	s_cbranch_execz .LBB0_312
	v_mov_b32_e32 v77, v0
	v_lshlrev_b64 v[2:3], s26, v[76:77]
	v_lshl_add_u64 v[2:3], v[2:3], 0, s[22:23]
	v_mov_b64_e32 v[32:33], s[38:39]
	s_movk_i32 s55, 0x4800
	v_mad_u64_u32 v[32:33], vcc, v2, s55, v[32:33]
	v_mov_b32_e32 v2, v33
	v_mad_u64_u32 v[2:3], vcc, v3, s55, v[2:3]
	v_mov_b32_e32 v33, v2
	v_mov_b32_e32 v79, v0
	v_lshl_add_u64 v[2:3], v[32:33], 0, v[78:79]
	v_add_co_u32_e32 v36, vcc, 0x1000, v2
	s_nop 1
	v_addc_co_u32_e32 v37, vcc, 0, v3, vcc
	global_load_dwordx4 v[32:35], v[2:3], off offset:2048
	s_nop 0
	global_load_dwordx4 v[36:39], v[36:37], off

.LBB0_318:
	s_or_b64 exec, exec, s[30:31]
	v_add_u32_e32 v2, s51, v147
	v_ashrrev_i32_e32 v3, 31, v2
	v_lshlrev_b64 v[2:3], s26, v[2:3]
	v_lshl_add_u64 v[2:3], v[2:3], 0, s[22:23]
	v_mov_b64_e32 v[76:77], s[34:35]
	s_movk_i32 s26, 0x4800
	v_mad_u64_u32 v[76:77], s[22:23], v2, s26, v[76:77]
	v_mov_b32_e32 v2, v77
	v_mad_u64_u32 v[2:3], s[22:23], v3, s26, v[2:3]
	v_mov_b32_e32 v77, v2
	v_lshl_add_u64 v[2:3], s[20:21], 1, v[76:77]
	v_mov_b32_e32 v135, v0
	v_lshl_add_u64 v[2:3], v[2:3], 0, v[134:135]
	global_load_dwordx4 v[76:79], v[2:3], off nt
	global_load_dwordx4 v[80:83], v[2:3], off offset:64 nt
